# down-proj: second round uses 128-row half tiles on all 256 blocks (unused half MFMAs/reads/stores skipped)
# baseline (speedup 1.0000x reference)
.LBB0_56:
	s_andn2_b64 vcc, exec, s[2:3]
	s_cbranch_vccnz .LBB0_73
	v_readlane_b32 s0, v255, 22
	s_cmpk_gt_i32 s0, 0x17f
	v_readlane_b32 s1, v255, 23
	s_cbranch_scc1 .LBB0_73
	s_mov_b32 s32, 0
	s_and_b64 s[0:1], s[48:49], exec
	s_mov_b32 s0, 0x1c80000
	s_cselect_b32 s0, s0, 0x12558000
	s_add_u32 s6, s72, s0
	v_readlane_b32 s0, v255, 22
	s_addc_u32 s7, s73, 0
	s_mov_b32 s10, s0
	v_readlane_b32 s1, v255, 23
	s_branch .LBB0_60
.LBB0_59:
	v_lshrrev_b32_e32 v0, 2, v140
	v_and_b32_e32 v0, 0x3fffc0, v0
	v_and_or_b32 v130, v140, 15, s12
	v_add_lshl_u32 v0, v130, v0, 10
	v_lshrrev_b32_e32 v130, 1, v140
	s_lshl_b32 s0, s11, 8
	v_and_b32_e32 v130, 0x78, v130
	v_or3_b32 v130, v0, s0, v130
	s_barrier
	v_readlane_b32 s0, v255, 26
	v_cvt_pk_bf16_f32 v62, v62, v63
	v_cvt_pk_bf16_f32 v63, v64, v65
	v_cvt_pk_bf16_f32 v64, v58, v59
	v_add_u32_e32 v58, 0x20080, v130
	v_ashrrev_i32_e32 v131, 31, v130
	v_readlane_b32 s1, v255, 27
	v_cvt_pk_bf16_f32 v110, v110, v111
	v_cvt_pk_bf16_f32 v111, v112, v113
	v_cvt_pk_bf16_f32 v112, v106, v107
	v_add_u32_e32 v106, 0x4000, v130
	v_ashrrev_i32_e32 v59, 31, v58
	v_cvt_pk_bf16_f32 v46, v46, v47
	v_cvt_pk_bf16_f32 v47, v48, v49
	v_cvt_pk_bf16_f32 v48, v42, v43
	v_add_u32_e32 v42, 0x24000, v130
	v_lshl_add_u64 v[132:133], v[130:131], 1, s[0:1]
	v_cvt_pk_bf16_f32 v113, v108, v109
	v_ashrrev_i32_e32 v107, 31, v106
	v_lshl_add_u64 v[58:59], v[58:59], 1, s[0:1]
	v_cvt_pk_bf16_f32 v49, v44, v45
	v_ashrrev_i32_e32 v43, 31, v42
	s_cmp_eq_u32 s32, 2
	s_cbranch_scc1 .Lh9_1
	global_store_dwordx4 v[132:133], v[110:113], off offset:256
.Lh9_1:
	v_cvt_pk_bf16_f32 v108, v114, v115
	v_cvt_pk_bf16_f32 v109, v116, v117
	v_lshl_add_u64 v[110:111], v[106:107], 1, s[0:1]
	v_cvt_pk_bf16_f32 v106, v118, v119
	v_cvt_pk_bf16_f32 v107, v120, v121
	s_cmp_eq_u32 s32, 1
	s_cbranch_scc1 .Lh9_2
	global_store_dwordx4 v[58:59], v[46:49], off
.Lh9_2:
	v_cvt_pk_bf16_f32 v44, v50, v51
	v_cvt_pk_bf16_f32 v45, v52, v53
	v_lshl_add_u64 v[46:47], v[42:43], 1, s[0:1]
	v_cvt_pk_bf16_f32 v42, v54, v55
	v_cvt_pk_bf16_f32 v43, v56, v57
	s_cmp_eq_u32 s32, 2
	s_cbranch_scc1 .Lh9_3
	global_store_dwordx4 v[110:111], v[106:109], off
.Lh9_3:
	s_cmp_eq_u32 s32, 1
	s_cbranch_scc1 .Lh9_4
	global_store_dwordx4 v[46:47], v[42:45], off
.Lh9_4:
	v_cvt_pk_bf16_f32 v94, v94, v95
	v_add_u32_e32 v106, 0x4080, v130
	v_add_u32_e32 v42, 0x24080, v130
	v_ashrrev_i32_e32 v107, 31, v106
	v_cvt_pk_bf16_f32 v95, v96, v97
	v_cvt_pk_bf16_f32 v96, v90, v91
	v_add_u32_e32 v90, 0x8000, v130
	v_ashrrev_i32_e32 v43, 31, v42
	v_cvt_pk_bf16_f32 v30, v30, v31
	v_cvt_pk_bf16_f32 v31, v32, v33
	v_cvt_pk_bf16_f32 v32, v26, v27
	v_add_u32_e32 v26, 0x28000, v130
	v_lshl_add_u64 v[106:107], v[106:107], 1, s[0:1]
	v_cvt_pk_bf16_f32 v97, v92, v93
	v_ashrrev_i32_e32 v91, 31, v90
	v_lshl_add_u64 v[42:43], v[42:43], 1, s[0:1]
	v_cvt_pk_bf16_f32 v33, v28, v29
	v_ashrrev_i32_e32 v27, 31, v26
	s_cmp_eq_u32 s32, 2
	s_cbranch_scc1 .Lh9_5
	global_store_dwordx4 v[106:107], v[94:97], off
.Lh9_5:
	v_cvt_pk_bf16_f32 v92, v98, v99
	v_cvt_pk_bf16_f32 v93, v100, v101
	v_lshl_add_u64 v[94:95], v[90:91], 1, s[0:1]
	v_cvt_pk_bf16_f32 v90, v102, v103
	v_cvt_pk_bf16_f32 v91, v104, v105
	s_cmp_eq_u32 s32, 1
	s_cbranch_scc1 .Lh9_6
	global_store_dwordx4 v[42:43], v[30:33], off
.Lh9_6:
	v_cvt_pk_bf16_f32 v28, v34, v35
	v_cvt_pk_bf16_f32 v29, v36, v37
	v_lshl_add_u64 v[30:31], v[26:27], 1, s[0:1]
	v_cvt_pk_bf16_f32 v26, v38, v39
	v_cvt_pk_bf16_f32 v27, v40, v41
	s_cmp_eq_u32 s32, 2
	s_cbranch_scc1 .Lh9_7
	global_store_dwordx4 v[94:95], v[90:93], off
.Lh9_7:
	s_cmp_eq_u32 s32, 1
	s_cbranch_scc1 .Lh9_8
	global_store_dwordx4 v[30:31], v[26:29], off
.Lh9_8:
	v_cvt_pk_bf16_f32 v78, v78, v79
	v_add_u32_e32 v90, 0x8080, v130
	v_add_u32_e32 v26, 0x28080, v130
	v_ashrrev_i32_e32 v91, 31, v90
	v_cvt_pk_bf16_f32 v79, v80, v81
	v_cvt_pk_bf16_f32 v80, v74, v75
	v_add_u32_e32 v74, 0xc000, v130
	v_ashrrev_i32_e32 v27, 31, v26
	v_cvt_pk_bf16_f32 v14, v14, v15
	v_cvt_pk_bf16_f32 v15, v16, v17
	v_cvt_pk_bf16_f32 v16, v10, v11
	v_add_u32_e32 v10, 0x2c000, v130
	v_lshl_add_u64 v[90:91], v[90:91], 1, s[0:1]
	v_cvt_pk_bf16_f32 v81, v76, v77
	v_ashrrev_i32_e32 v75, 31, v74
	v_lshl_add_u64 v[26:27], v[26:27], 1, s[0:1]
	v_cvt_pk_bf16_f32 v17, v12, v13
	v_ashrrev_i32_e32 v11, 31, v10
	s_cmp_eq_u32 s32, 2
	s_cbranch_scc1 .Lh9_9
	global_store_dwordx4 v[90:91], v[78:81], off
.Lh9_9:
	v_cvt_pk_bf16_f32 v76, v82, v83
	v_cvt_pk_bf16_f32 v77, v84, v85
	v_lshl_add_u64 v[78:79], v[74:75], 1, s[0:1]
	v_cvt_pk_bf16_f32 v74, v86, v87
	v_cvt_pk_bf16_f32 v75, v88, v89
	s_cmp_eq_u32 s32, 1
	s_cbranch_scc1 .Lh9_10
	global_store_dwordx4 v[26:27], v[14:17], off
.Lh9_10:
	v_cvt_pk_bf16_f32 v12, v18, v19
	v_cvt_pk_bf16_f32 v13, v20, v21
	v_lshl_add_u64 v[14:15], v[10:11], 1, s[0:1]
	v_cvt_pk_bf16_f32 v10, v22, v23
	v_cvt_pk_bf16_f32 v11, v24, v25
	s_cmp_eq_u32 s32, 2
	s_cbranch_scc1 .Lh9_11
	global_store_dwordx4 v[78:79], v[74:77], off
.Lh9_11:
	v_cvt_pk_bf16_f32 v70, v70, v71
	v_cvt_pk_bf16_f32 v71, v72, v73
	v_add_u32_e32 v74, 0xc080, v130
	v_cvt_pk_bf16_f32 v72, v66, v67
	v_add_u32_e32 v66, 0x20000, v130
	s_cmp_eq_u32 s32, 1
	s_cbranch_scc1 .Lh9_12
	global_store_dwordx4 v[14:15], v[10:13], off
.Lh9_12:
	v_ashrrev_i32_e32 v75, 31, v74
	v_ashrrev_i32_e32 v67, 31, v66
	v_add_u32_e32 v10, 0x2c080, v130
	v_ashrrev_i32_e32 v11, 31, v10
	v_cvt_pk_bf16_f32 v126, v126, v127
	v_cvt_pk_bf16_f32 v127, v128, v129
	v_cvt_pk_bf16_f32 v128, v122, v123
	v_cvt_pk_bf16_f32 v129, v124, v125
	v_lshl_add_u64 v[74:75], v[74:75], 1, s[0:1]
	v_cvt_pk_bf16_f32 v73, v68, v69
	v_lshl_add_u64 v[66:67], v[66:67], 1, s[0:1]
	v_cvt_pk_bf16_f32 v65, v60, v61
	v_lshl_add_u64 v[10:11], v[10:11], 1, s[0:1]
	v_cvt_pk_bf16_f32 v6, v6, v7
	v_cvt_pk_bf16_f32 v7, v8, v9
	v_cvt_pk_bf16_f32 v8, v2, v3
	v_cvt_pk_bf16_f32 v9, v4, v5
	s_movk_i32 s58, 0x21ff
	s_cmp_eq_u32 s32, 2
	s_cbranch_scc1 .Lh9_13
	global_store_dwordx4 v[132:133], v[126:129], off
.Lh9_13:
	s_cmp_eq_u32 s32, 2
	s_cbranch_scc1 .Lh9_14
	global_store_dwordx4 v[74:75], v[70:73], off
.Lh9_14:
	s_cmp_eq_u32 s32, 1
	s_cbranch_scc1 .Lh9_15
	global_store_dwordx4 v[66:67], v[62:65], off
.Lh9_15:
	s_cmp_eq_u32 s32, 1
	s_cbranch_scc1 .Lh9_16
	global_store_dwordx4 v[10:11], v[6:9], off
.Lh9_16:
	s_cmpk_lg_i32 s89, 0x100
	s_cbranch_scc1 .Lh9_generic
	s_cmp_lg_u32 s32, 0
	s_cbranch_scc1 .Lh9_exit
	v_readlane_b32 s13, v255, 22
	s_and_b32 s32, s13, 1
	s_add_u32 s32, s32, 1
	s_lshr_b32 s13, s13, 1
	s_add_u32 s10, s13, 0x100
	s_branch .LBB0_60
.Lh9_exit:
	s_mov_b32 s32, 0
	s_branch .LBB0_73
.Lh9_generic:
	s_add_i32 s10, s10, s89
	s_cmpk_gt_i32 s10, 0x17f
	s_cbranch_scc1 .LBB0_73

.LBB0_70:
	s_add_u32 s18, s8, 0xf9e08080
	s_addc_u32 s19, s9, -1
	s_cmp_lg_u32 s58, 40
	s_cselect_b32 s18, s18, 0
	s_cselect_b32 s19, s19, 0
	s_add_u32 s40, s0, s18
	s_addc_u32 s41, s1, s19
	s_add_i32 s20, 0, 0x10000
	s_add_u32 s18, s2, s18
	v_add_u32_e32 v143, s20, v141
	s_addc_u32 s19, s3, s19
	s_add_i32 s59, 0, 0x14000
	ds_read_b128 v[144:147], v143
	ds_read_b128 v[148:151], v143 offset:1024
	ds_read_b128 v[152:155], v143 offset:2048
	ds_read_b128 v[158:161], v143 offset:3072
	v_add_u32_e32 v143, s59, v141
	ds_read_b128 v[162:165], v143
	ds_read_b128 v[196:199], v143 offset:1024
	ds_read_b128 v[200:203], v143 offset:2048
	ds_read_b128 v[204:207], v143 offset:3072
	v_lshl_add_u64 v[176:177], v[138:139], 0, s[8:9]
	s_add_i32 m0, s17, 0xc000
	s_cmp_eq_u32 s32, 2
	s_cbranch_scc1 .Lh9_17
	ds_read_b128 v[208:211], v142
	ds_read_b128 v[212:215], v142 offset:1024
	ds_read_b128 v[216:219], v142 offset:2048
	ds_read_b128 v[220:223], v142 offset:3072
	ds_read_b128 v[224:227], v142 offset:4096
	ds_read_b128 v[228:231], v142 offset:5120
	ds_read_b128 v[232:235], v142 offset:6144
	ds_read_b128 v[236:239], v142 offset:7168
.Lh9_17:
	global_load_lds_dwordx4 v[176:177], off
	v_lshl_add_u64 v[176:177], v[136:137], 0, s[8:9]
	s_add_i32 m0, s17, 0xe000
	s_nop 0
	global_load_lds_dwordx4 v[176:177], off
	s_waitcnt vmcnt(8)
	s_waitcnt lgkmcnt(0)
	s_barrier
	s_cmp_eq_u32 s32, 2
	s_cbranch_scc1 .Lh9_18
	s_setprio 1
	s_waitcnt lgkmcnt(0)
	v_mfma_f32_16x16x32_bf16 v[126:129], v[144:147], v[208:211], v[126:129]
	v_mfma_f32_16x16x32_bf16 v[122:125], v[152:155], v[208:211], v[122:125]
	v_mfma_f32_16x16x32_bf16 v[118:121], v[144:147], v[216:219], v[118:121]
	v_mfma_f32_16x16x32_bf16 v[114:117], v[152:155], v[216:219], v[114:117]
	v_mfma_f32_16x16x32_bf16 v[102:105], v[144:147], v[224:227], v[102:105]
	v_mfma_f32_16x16x32_bf16 v[98:101], v[152:155], v[224:227], v[98:101]
	v_mfma_f32_16x16x32_bf16 v[86:89], v[144:147], v[232:235], v[86:89]
	v_mfma_f32_16x16x32_bf16 v[82:85], v[152:155], v[232:235], v[82:85]
	v_mfma_f32_16x16x32_bf16 v[126:129], v[148:151], v[212:215], v[126:129]
	v_mfma_f32_16x16x32_bf16 v[122:125], v[158:161], v[212:215], v[122:125]
	v_mfma_f32_16x16x32_bf16 v[118:121], v[148:151], v[220:223], v[118:121]
	v_mfma_f32_16x16x32_bf16 v[114:117], v[158:161], v[220:223], v[114:117]
	v_mfma_f32_16x16x32_bf16 v[102:105], v[148:151], v[228:231], v[102:105]
	v_mfma_f32_16x16x32_bf16 v[98:101], v[158:161], v[228:231], v[98:101]
	v_mfma_f32_16x16x32_bf16 v[86:89], v[148:151], v[236:239], v[86:89]
	v_mfma_f32_16x16x32_bf16 v[82:85], v[158:161], v[236:239], v[82:85]
	s_setprio 0
	s_setprio 1
	v_mfma_f32_16x16x32_bf16 v[110:113], v[162:165], v[208:211], v[110:113]
	v_mfma_f32_16x16x32_bf16 v[106:109], v[200:203], v[208:211], v[106:109]
	v_mfma_f32_16x16x32_bf16 v[94:97], v[162:165], v[216:219], v[94:97]
	v_mfma_f32_16x16x32_bf16 v[90:93], v[200:203], v[216:219], v[90:93]
	v_mfma_f32_16x16x32_bf16 v[78:81], v[162:165], v[224:227], v[78:81]
	v_mfma_f32_16x16x32_bf16 v[74:77], v[200:203], v[224:227], v[74:77]
	v_mfma_f32_16x16x32_bf16 v[70:73], v[162:165], v[232:235], v[70:73]
	v_mfma_f32_16x16x32_bf16 v[66:69], v[200:203], v[232:235], v[66:69]
	v_mfma_f32_16x16x32_bf16 v[110:113], v[196:199], v[212:215], v[110:113]
	v_mfma_f32_16x16x32_bf16 v[106:109], v[204:207], v[212:215], v[106:109]
	v_mfma_f32_16x16x32_bf16 v[94:97], v[196:199], v[220:223], v[94:97]
	v_mfma_f32_16x16x32_bf16 v[90:93], v[204:207], v[220:223], v[90:93]
	v_mfma_f32_16x16x32_bf16 v[78:81], v[196:199], v[228:231], v[78:81]
	v_mfma_f32_16x16x32_bf16 v[74:77], v[204:207], v[228:231], v[74:77]
	v_mfma_f32_16x16x32_bf16 v[70:73], v[196:199], v[236:239], v[70:73]
	v_mfma_f32_16x16x32_bf16 v[66:69], v[204:207], v[236:239], v[66:69]
	s_setprio 0
.Lh9_18:
	s_barrier
	s_add_i32 s20, s20, s16
	v_lshl_add_u64 v[176:177], s[18:19], 0, v[0:1]
	s_mov_b32 m0, s20
	s_cmp_eq_u32 s32, 1
	s_cbranch_scc1 .Lh9_19
	ds_read_b128 v[208:211], v142 offset:16384
	ds_read_b128 v[212:215], v142 offset:17408
	ds_read_b128 v[216:219], v142 offset:18432
	ds_read_b128 v[220:223], v142 offset:19456
	ds_read_b128 v[224:227], v142 offset:20480
	ds_read_b128 v[228:231], v142 offset:21504
	ds_read_b128 v[232:235], v142 offset:22528
	ds_read_b128 v[236:239], v142 offset:23552
.Lh9_19:
	global_load_lds_dwordx4 v[176:177], off
	s_add_i32 m0, s20, 0x2000
	s_add_u32 s62, s18, 0xb0000
	v_lshl_add_u64 v[178:179], s[18:19], 0, v[134:135]
	s_addc_u32 s63, s19, 0
	s_add_i32 s20, s59, s16
	global_load_lds_dwordx4 v[178:179], off
	v_lshl_add_u64 v[194:195], s[62:63], 0, v[0:1]
	s_mov_b32 m0, s20
	v_lshl_add_u64 v[240:241], s[40:41], 0, v[132:133]
	global_load_lds_dwordx4 v[194:195], off
	v_lshl_add_u64 v[194:195], s[62:63], 0, v[134:135]
	s_add_i32 m0, s20, 0x2000
	s_nop 0
	global_load_lds_dwordx4 v[194:195], off
	v_lshl_add_u64 v[194:195], s[40:41], 0, v[130:131]
	s_mov_b32 m0, s17
	s_nop 0
	global_load_lds_dwordx4 v[194:195], off
	s_mov_b32 m0, s28
	s_nop 0
	global_load_lds_dwordx4 v[240:241], off
	s_waitcnt vmcnt(8)
	s_waitcnt lgkmcnt(0)
	s_barrier
	s_cmp_eq_u32 s32, 1
	s_cbranch_scc1 .Lh9_20
	s_setprio 1
	s_waitcnt lgkmcnt(0)
	v_mfma_f32_16x16x32_bf16 v[62:65], v[144:147], v[208:211], v[62:65]
	v_mfma_f32_16x16x32_bf16 v[58:61], v[152:155], v[208:211], v[58:61]
	v_mfma_f32_16x16x32_bf16 v[54:57], v[144:147], v[216:219], v[54:57]
	v_mfma_f32_16x16x32_bf16 v[50:53], v[152:155], v[216:219], v[50:53]
	v_mfma_f32_16x16x32_bf16 v[38:41], v[144:147], v[224:227], v[38:41]
	v_mfma_f32_16x16x32_bf16 v[34:37], v[152:155], v[224:227], v[34:37]
	v_mfma_f32_16x16x32_bf16 v[22:25], v[144:147], v[232:235], v[22:25]
	v_mfma_f32_16x16x32_bf16 v[18:21], v[152:155], v[232:235], v[18:21]
	v_mfma_f32_16x16x32_bf16 v[62:65], v[148:151], v[212:215], v[62:65]
	v_mfma_f32_16x16x32_bf16 v[58:61], v[158:161], v[212:215], v[58:61]
	v_mfma_f32_16x16x32_bf16 v[54:57], v[148:151], v[220:223], v[54:57]
	v_mfma_f32_16x16x32_bf16 v[50:53], v[158:161], v[220:223], v[50:53]
	v_mfma_f32_16x16x32_bf16 v[38:41], v[148:151], v[228:231], v[38:41]
	v_mfma_f32_16x16x32_bf16 v[34:37], v[158:161], v[228:231], v[34:37]
	v_mfma_f32_16x16x32_bf16 v[22:25], v[148:151], v[236:239], v[22:25]
	v_mfma_f32_16x16x32_bf16 v[18:21], v[158:161], v[236:239], v[18:21]
	s_setprio 0
	s_setprio 1
	v_mfma_f32_16x16x32_bf16 v[46:49], v[162:165], v[208:211], v[46:49]
	v_mfma_f32_16x16x32_bf16 v[42:45], v[200:203], v[208:211], v[42:45]
	v_mfma_f32_16x16x32_bf16 v[30:33], v[162:165], v[216:219], v[30:33]
	v_mfma_f32_16x16x32_bf16 v[26:29], v[200:203], v[216:219], v[26:29]
	v_mfma_f32_16x16x32_bf16 v[14:17], v[162:165], v[224:227], v[14:17]
	v_mfma_f32_16x16x32_bf16 v[10:13], v[200:203], v[224:227], v[10:13]
	v_mfma_f32_16x16x32_bf16 v[6:9], v[162:165], v[232:235], v[6:9]
	v_mfma_f32_16x16x32_bf16 v[2:5], v[200:203], v[232:235], v[2:5]
	v_mfma_f32_16x16x32_bf16 v[46:49], v[196:199], v[212:215], v[46:49]
	v_mfma_f32_16x16x32_bf16 v[42:45], v[204:207], v[212:215], v[42:45]
	v_mfma_f32_16x16x32_bf16 v[30:33], v[196:199], v[220:223], v[30:33]
	v_mfma_f32_16x16x32_bf16 v[26:29], v[204:207], v[220:223], v[26:29]
	v_mfma_f32_16x16x32_bf16 v[14:17], v[196:199], v[228:231], v[14:17]
	v_mfma_f32_16x16x32_bf16 v[10:13], v[204:207], v[228:231], v[10:13]
	v_mfma_f32_16x16x32_bf16 v[6:9], v[196:199], v[236:239], v[6:9]
	v_mfma_f32_16x16x32_bf16 v[2:5], v[204:207], v[236:239], v[2:5]
	s_setprio 0
.Lh9_20:
	s_barrier
	s_add_i32 s20, 0, 0x18000
	v_add_u32_e32 v143, s20, v141
	s_add_i32 s59, 0, 0x1c000
	ds_read_b128 v[144:147], v143
	ds_read_b128 v[148:151], v143 offset:1024
	ds_read_b128 v[152:155], v143 offset:2048
	ds_read_b128 v[158:161], v143 offset:3072
	v_add_u32_e32 v143, s59, v141
	ds_read_b128 v[162:165], v143
	ds_read_b128 v[196:199], v143 offset:1024
	ds_read_b128 v[200:203], v143 offset:2048
	ds_read_b128 v[204:207], v143 offset:3072
	s_add_u32 s40, s40, 0xb0000
	s_addc_u32 s41, s41, 0
	s_mov_b32 m0, s42
	v_lshl_add_u64 v[242:243], s[40:41], 0, v[130:131]
	s_cmp_eq_u32 s32, 2
	s_cbranch_scc1 .Lh9_21
	ds_read_b128 v[208:211], v142 offset:32768
	ds_read_b128 v[212:215], v142 offset:33792
	ds_read_b128 v[216:219], v142 offset:34816
	ds_read_b128 v[220:223], v142 offset:35840
	ds_read_b128 v[224:227], v142 offset:36864
	ds_read_b128 v[228:231], v142 offset:37888
	ds_read_b128 v[232:235], v142 offset:38912
	ds_read_b128 v[236:239], v142 offset:39936
.Lh9_21:
	global_load_lds_dwordx4 v[242:243], off
	v_lshl_add_u64 v[242:243], s[40:41], 0, v[132:133]
	s_mov_b32 m0, s43
	s_nop 0
	global_load_lds_dwordx4 v[242:243], off
	s_waitcnt vmcnt(8)
	s_waitcnt lgkmcnt(0)
	s_barrier
	s_cmp_eq_u32 s32, 2
	s_cbranch_scc1 .Lh9_22
	s_setprio 1
	s_waitcnt lgkmcnt(0)
	v_mfma_f32_16x16x32_bf16 v[126:129], v[144:147], v[208:211], v[126:129]
	v_mfma_f32_16x16x32_bf16 v[122:125], v[152:155], v[208:211], v[122:125]
	v_mfma_f32_16x16x32_bf16 v[118:121], v[144:147], v[216:219], v[118:121]
	v_mfma_f32_16x16x32_bf16 v[114:117], v[152:155], v[216:219], v[114:117]
	v_mfma_f32_16x16x32_bf16 v[102:105], v[144:147], v[224:227], v[102:105]
	v_mfma_f32_16x16x32_bf16 v[98:101], v[152:155], v[224:227], v[98:101]
	v_mfma_f32_16x16x32_bf16 v[86:89], v[144:147], v[232:235], v[86:89]
	v_mfma_f32_16x16x32_bf16 v[82:85], v[152:155], v[232:235], v[82:85]
	v_mfma_f32_16x16x32_bf16 v[126:129], v[148:151], v[212:215], v[126:129]
	v_mfma_f32_16x16x32_bf16 v[122:125], v[158:161], v[212:215], v[122:125]
	v_mfma_f32_16x16x32_bf16 v[118:121], v[148:151], v[220:223], v[118:121]
	v_mfma_f32_16x16x32_bf16 v[114:117], v[158:161], v[220:223], v[114:117]
	v_mfma_f32_16x16x32_bf16 v[102:105], v[148:151], v[228:231], v[102:105]
	v_mfma_f32_16x16x32_bf16 v[98:101], v[158:161], v[228:231], v[98:101]
	v_mfma_f32_16x16x32_bf16 v[86:89], v[148:151], v[236:239], v[86:89]
	v_mfma_f32_16x16x32_bf16 v[82:85], v[158:161], v[236:239], v[82:85]
	s_setprio 0
	s_setprio 1
	v_mfma_f32_16x16x32_bf16 v[110:113], v[162:165], v[208:211], v[110:113]
	v_mfma_f32_16x16x32_bf16 v[106:109], v[200:203], v[208:211], v[106:109]
	v_mfma_f32_16x16x32_bf16 v[94:97], v[162:165], v[216:219], v[94:97]
	v_mfma_f32_16x16x32_bf16 v[90:93], v[200:203], v[216:219], v[90:93]
	v_mfma_f32_16x16x32_bf16 v[78:81], v[162:165], v[224:227], v[78:81]
	v_mfma_f32_16x16x32_bf16 v[74:77], v[200:203], v[224:227], v[74:77]
	v_mfma_f32_16x16x32_bf16 v[70:73], v[162:165], v[232:235], v[70:73]
	v_mfma_f32_16x16x32_bf16 v[66:69], v[200:203], v[232:235], v[66:69]
	v_mfma_f32_16x16x32_bf16 v[110:113], v[196:199], v[212:215], v[110:113]
	v_mfma_f32_16x16x32_bf16 v[106:109], v[204:207], v[212:215], v[106:109]
	v_mfma_f32_16x16x32_bf16 v[94:97], v[196:199], v[220:223], v[94:97]
	v_mfma_f32_16x16x32_bf16 v[90:93], v[204:207], v[220:223], v[90:93]
	v_mfma_f32_16x16x32_bf16 v[78:81], v[196:199], v[228:231], v[78:81]
	v_mfma_f32_16x16x32_bf16 v[74:77], v[204:207], v[228:231], v[74:77]
	v_mfma_f32_16x16x32_bf16 v[70:73], v[196:199], v[236:239], v[70:73]
	v_mfma_f32_16x16x32_bf16 v[66:69], v[204:207], v[236:239], v[66:69]
	s_setprio 0
.Lh9_22:
	s_barrier
	s_add_i32 s20, s20, s16
	v_lshl_add_u64 v[176:177], v[176:177], 0, s[24:25]
	s_mov_b32 m0, s20
	s_cmp_eq_u32 s32, 1
	s_cbranch_scc1 .Lh9_23
	ds_read_b128 v[208:211], v142 offset:49152
	ds_read_b128 v[212:215], v142 offset:50176
	ds_read_b128 v[216:219], v142 offset:51200
	ds_read_b128 v[220:223], v142 offset:52224
	ds_read_b128 v[224:227], v142 offset:53248
	ds_read_b128 v[228:231], v142 offset:54272
	ds_read_b128 v[232:235], v142 offset:55296
	ds_read_b128 v[236:239], v142 offset:56320
.Lh9_23:
	global_load_lds_dwordx4 v[176:177], off
	s_add_i32 m0, s20, 0x2000
	s_add_u32 s18, s18, 0xb0080
	v_lshl_add_u64 v[176:177], v[178:179], 0, s[24:25]
	s_addc_u32 s19, s19, 0
	s_add_i32 s20, s59, s16
	global_load_lds_dwordx4 v[176:177], off
	v_lshl_add_u64 v[176:177], s[18:19], 0, v[0:1]
	s_mov_b32 m0, s20
	s_nop 0
	global_load_lds_dwordx4 v[176:177], off
	v_lshl_add_u64 v[176:177], s[18:19], 0, v[134:135]
	s_add_i32 m0, s20, 0x2000
	s_nop 0
	global_load_lds_dwordx4 v[176:177], off
	v_lshl_add_u64 v[176:177], v[194:195], 0, s[24:25]
	s_mov_b32 m0, s46
	s_nop 0
	global_load_lds_dwordx4 v[176:177], off
	v_lshl_add_u64 v[176:177], v[240:241], 0, s[24:25]
	s_mov_b32 m0, s47
	s_nop 0
	global_load_lds_dwordx4 v[176:177], off
	s_waitcnt vmcnt(8)
	s_waitcnt lgkmcnt(0)
	s_barrier
	s_cmp_eq_u32 s32, 1
	s_cbranch_scc1 .Lh9_24
	s_setprio 1
	s_waitcnt lgkmcnt(0)
	v_mfma_f32_16x16x32_bf16 v[62:65], v[144:147], v[208:211], v[62:65]
	v_mfma_f32_16x16x32_bf16 v[58:61], v[152:155], v[208:211], v[58:61]
	v_mfma_f32_16x16x32_bf16 v[54:57], v[144:147], v[216:219], v[54:57]
	v_mfma_f32_16x16x32_bf16 v[50:53], v[152:155], v[216:219], v[50:53]
	v_mfma_f32_16x16x32_bf16 v[38:41], v[144:147], v[224:227], v[38:41]
	v_mfma_f32_16x16x32_bf16 v[34:37], v[152:155], v[224:227], v[34:37]
	v_mfma_f32_16x16x32_bf16 v[22:25], v[144:147], v[232:235], v[22:25]
	v_mfma_f32_16x16x32_bf16 v[18:21], v[152:155], v[232:235], v[18:21]
	v_mfma_f32_16x16x32_bf16 v[62:65], v[148:151], v[212:215], v[62:65]
	v_mfma_f32_16x16x32_bf16 v[58:61], v[158:161], v[212:215], v[58:61]
	v_mfma_f32_16x16x32_bf16 v[54:57], v[148:151], v[220:223], v[54:57]
	v_mfma_f32_16x16x32_bf16 v[50:53], v[158:161], v[220:223], v[50:53]
	v_mfma_f32_16x16x32_bf16 v[38:41], v[148:151], v[228:231], v[38:41]
	v_mfma_f32_16x16x32_bf16 v[34:37], v[158:161], v[228:231], v[34:37]
	v_mfma_f32_16x16x32_bf16 v[22:25], v[148:151], v[236:239], v[22:25]
	v_mfma_f32_16x16x32_bf16 v[18:21], v[158:161], v[236:239], v[18:21]
	s_setprio 0
	s_setprio 1
	v_mfma_f32_16x16x32_bf16 v[46:49], v[162:165], v[208:211], v[46:49]
	v_mfma_f32_16x16x32_bf16 v[42:45], v[200:203], v[208:211], v[42:45]
	v_mfma_f32_16x16x32_bf16 v[30:33], v[162:165], v[216:219], v[30:33]
	v_mfma_f32_16x16x32_bf16 v[26:29], v[200:203], v[216:219], v[26:29]
	v_mfma_f32_16x16x32_bf16 v[14:17], v[162:165], v[224:227], v[14:17]
	v_mfma_f32_16x16x32_bf16 v[10:13], v[200:203], v[224:227], v[10:13]
	v_mfma_f32_16x16x32_bf16 v[6:9], v[162:165], v[232:235], v[6:9]
	v_mfma_f32_16x16x32_bf16 v[2:5], v[200:203], v[232:235], v[2:5]
	v_mfma_f32_16x16x32_bf16 v[46:49], v[196:199], v[212:215], v[46:49]
	v_mfma_f32_16x16x32_bf16 v[42:45], v[204:207], v[212:215], v[42:45]
	v_mfma_f32_16x16x32_bf16 v[30:33], v[196:199], v[220:223], v[30:33]
	v_mfma_f32_16x16x32_bf16 v[26:29], v[204:207], v[220:223], v[26:29]
	v_mfma_f32_16x16x32_bf16 v[14:17], v[196:199], v[228:231], v[14:17]
	v_mfma_f32_16x16x32_bf16 v[10:13], v[204:207], v[228:231], v[10:13]
	v_mfma_f32_16x16x32_bf16 v[6:9], v[196:199], v[236:239], v[6:9]
	v_mfma_f32_16x16x32_bf16 v[2:5], v[204:207], v[236:239], v[2:5]
	s_setprio 0
.Lh9_24:
	s_barrier
	s_add_i32 s58, s58, 2
	s_add_u32 s8, s8, 0x100
	s_addc_u32 s9, s9, 0
	s_cmp_gt_u32 s58, 41
	s_cbranch_scc0 .LBB0_70
	s_waitcnt vmcnt(0)
	s_cmpk_lt_u32 s13, 0x100
	s_cbranch_scc0 .LBB0_59
	s_barrier
	s_branch .LBB0_59
